# on top of the 1.032x version: NSA selected/window tile loops issue all eight K-fragment LDS reads of a QK tile before the MFMA chain (unused registers, counted waits, same accumulate order)
# speedup vs baseline: 1.0006x; 1.0006x over previous
; #define MFMA32(a, b, c) __builtin_amdgcn_mfma_f32_32x32x16_bf16((a), (b), (c), 0, 0, 0)
; DI void qk_tile(const bf16_t* KT, const bf16x8 (&qf)[4], int qi, int hl, f32x16& sc0, f32x16& sc1) {
; #pragma unroll
;     for (int i = 0; i < 16; ++i) { sc0[i] = 0.f; sc1[i] = 0.f; }
; #pragma unroll
;     for (int s = 0; s < 4; ++s) {
;         const bf16x8 k0 = *(const bf16x8*)(KT + qi * KTS + 16 * s + 8 * hl), k1 = *(const bf16x8*)(KT + (32 + qi) * KTS + 16 * s + 8 * hl);
;         sc0 = MFMA32(k0, qf[s], sc0); sc1 = MFMA32(k1, qf[s], sc1);
;     }
; template <bool LUTB, bool CAUSAL, bool WHI, bool SEL>
; DI void mask_tile(f32x16& sc0, f32x16& sc1, const float* lut, int qpos, int k0, int hl, bool sel, float qs) {
;     const float bfar = lut[128];
; #pragma unroll
;     for (int g8 = 0; g8 < 2; ++g8) {
;         float ba[8], bb[8];
; #pragma unroll
;         for (int j = 0; j < 8; ++j) { const int i = g8 * 8 + j, kl = (i & 3) + 8 * (i >> 2) + 4 * hl; const int da = qpos - (k0 + kl), db = da - 32;
;             ba[j] = LUTB ? lut[da > 128 ? 128 : (da < 0 ? 0 : da)] : bfar; bb[j] = LUTB ? lut[db > 128 ? 128 : (db < 0 ? 0 : db)] : bfar; }
;         if (LUTB) asm volatile("" ::: "memory");
; #pragma unroll
;         for (int j = 0; j < 8; ++j) { const int i = g8 * 8 + j, kl = (i & 3) + 8 * (i >> 2) + 4 * hl; const int da = qpos - (k0 + kl), db = da - 32;
;             { const float v = sc0[i] * qs + ba[j]; bool ok = true; if (CAUSAL) ok = ok && da >= 0; if (WHI) ok = ok && da < 256; if (SEL) ok = ok && sel; sc0[i] = ok ? v : -INFINITY; }
;             { const float v = sc1[i] * qs + bb[j]; bool ok = true; if (CAUSAL) ok = ok && db >= 0; if (WHI) ok = ok && db < 256; if (SEL) ok = ok && sel; sc1[i] = ok ? v : -INFINITY; } }
.LBB0_776:
	s_or_b64 exec, exec, s[0:1]
	v_lshrrev_b32_e32 v0, v154, v141
	v_and_b32_e32 v0, 1, v0
	v_cmp_eq_u32_e64 s[0:1], 1, v0
	v_bfe_u32 v0, v141, v154, 1
	v_cmp_ne_u32_e32 vcc, 0, v0
	s_cbranch_vccz .LBB0_782
	ds_read_b128 v[180:183], v146 offset:4608
	ds_read_b128 v[184:187], v146
	ds_read_b128 v[188:191], v146 offset:32
	ds_read_b128 v[216:219], v146 offset:4640
	ds_read_b128 v[220:223], v146 offset:64
	ds_read_b128 v[224:227], v146 offset:4672
	ds_read_b128 v[228:231], v146 offset:96
	ds_read_b128 v[232:235], v146 offset:4704
	v_cmp_le_i32_e32 vcc, v154, v145
	s_waitcnt lgkmcnt(7)
	v_mfma_f32_32x32x16_bf16 v[66:81], v[180:183], v[98:101], 0
	s_waitcnt lgkmcnt(6)
	v_mfma_f32_32x32x16_bf16 v[82:97], v[184:187], v[98:101], 0
	s_waitcnt lgkmcnt(5)
	v_mfma_f32_32x32x16_bf16 v[82:97], v[188:191], v[102:105], v[82:97]
	s_waitcnt lgkmcnt(4)
	v_mfma_f32_32x32x16_bf16 v[66:81], v[216:219], v[102:105], v[66:81]
	s_waitcnt lgkmcnt(3)
	v_mfma_f32_32x32x16_bf16 v[82:97], v[220:223], v[106:109], v[82:97]
	s_waitcnt lgkmcnt(2)
	v_mfma_f32_32x32x16_bf16 v[66:81], v[224:227], v[106:109], v[66:81]
	s_waitcnt lgkmcnt(1)
	v_mfma_f32_32x32x16_bf16 v[82:97], v[228:231], v[110:113], v[82:97]
	s_waitcnt lgkmcnt(0)
	v_mfma_f32_32x32x16_bf16 v[66:81], v[232:235], v[110:113], v[66:81]
	s_and_saveexec_b64 s[10:11], vcc
	s_xor_b64 s[10:11], exec, s[10:11]
	s_cbranch_execz .LBB0_779
	ds_read_b32 v0, v129 offset:18944
	s_waitcnt lgkmcnt(0)
	s_nop 4
	v_fmamk_f32 v36, v83, 0x3e38aa3b, v0
	v_fmamk_f32 v34, v82, 0x3e38aa3b, v0
	v_fmamk_f32 v35, v66, 0x3e38aa3b, v0
	v_cndmask_b32_e64 v51, v247, v36, s[0:1]
	v_fmamk_f32 v36, v84, 0x3e38aa3b, v0
	v_fmamk_f32 v37, v85, 0x3e38aa3b, v0
	v_fmamk_f32 v38, v86, 0x3e38aa3b, v0
	v_fmamk_f32 v39, v87, 0x3e38aa3b, v0
	v_fmamk_f32 v40, v88, 0x3e38aa3b, v0
	v_fmamk_f32 v41, v89, 0x3e38aa3b, v0
	v_fmamk_f32 v42, v90, 0x3e38aa3b, v0
	v_fmamk_f32 v43, v91, 0x3e38aa3b, v0
	v_fmamk_f32 v44, v92, 0x3e38aa3b, v0
	v_fmamk_f32 v45, v93, 0x3e38aa3b, v0
	v_fmamk_f32 v46, v94, 0x3e38aa3b, v0
	v_fmamk_f32 v47, v95, 0x3e38aa3b, v0
	v_fmamk_f32 v48, v96, 0x3e38aa3b, v0
	v_cndmask_b32_e64 v50, v247, v34, s[0:1]
	v_cndmask_b32_e64 v34, v247, v35, s[0:1]
	v_fmamk_f32 v35, v67, 0x3e38aa3b, v0
	v_cndmask_b32_e64 v52, v247, v36, s[0:1]
	v_fmamk_f32 v36, v68, 0x3e38aa3b, v0
	v_cndmask_b32_e64 v53, v247, v37, s[0:1]
	v_fmamk_f32 v37, v69, 0x3e38aa3b, v0
	v_cndmask_b32_e64 v54, v247, v38, s[0:1]
	v_fmamk_f32 v38, v70, 0x3e38aa3b, v0
	v_cndmask_b32_e64 v55, v247, v39, s[0:1]
	v_fmamk_f32 v39, v71, 0x3e38aa3b, v0
	v_cndmask_b32_e64 v56, v247, v40, s[0:1]
	v_fmamk_f32 v40, v72, 0x3e38aa3b, v0
	v_cndmask_b32_e64 v57, v247, v41, s[0:1]
	v_fmamk_f32 v41, v73, 0x3e38aa3b, v0
	v_cndmask_b32_e64 v58, v247, v42, s[0:1]
	v_fmamk_f32 v42, v74, 0x3e38aa3b, v0
	v_cndmask_b32_e64 v59, v247, v43, s[0:1]
	v_fmamk_f32 v43, v75, 0x3e38aa3b, v0
	v_cndmask_b32_e64 v60, v247, v44, s[0:1]
	v_fmamk_f32 v44, v76, 0x3e38aa3b, v0
	v_cndmask_b32_e64 v61, v247, v45, s[0:1]
	v_fmamk_f32 v45, v77, 0x3e38aa3b, v0
	v_cndmask_b32_e64 v62, v247, v46, s[0:1]
	v_fmamk_f32 v46, v78, 0x3e38aa3b, v0
	v_cndmask_b32_e64 v63, v247, v47, s[0:1]
	v_fmamk_f32 v47, v79, 0x3e38aa3b, v0
	v_cndmask_b32_e64 v64, v247, v48, s[0:1]
	v_fmamk_f32 v48, v80, 0x3e38aa3b, v0
	v_fmamk_f32 v49, v97, 0x3e38aa3b, v0
	v_fmac_f32_e32 v0, 0x3e38aa3b, v81
	v_cndmask_b32_e64 v35, v247, v35, s[0:1]
	v_cndmask_b32_e64 v36, v247, v36, s[0:1]
	v_cndmask_b32_e64 v37, v247, v37, s[0:1]
	v_cndmask_b32_e64 v38, v247, v38, s[0:1]
	v_cndmask_b32_e64 v39, v247, v39, s[0:1]
	v_cndmask_b32_e64 v40, v247, v40, s[0:1]
	v_cndmask_b32_e64 v41, v247, v41, s[0:1]
	v_cndmask_b32_e64 v42, v247, v42, s[0:1]
	v_cndmask_b32_e64 v43, v247, v43, s[0:1]
	v_cndmask_b32_e64 v44, v247, v44, s[0:1]
	v_cndmask_b32_e64 v45, v247, v45, s[0:1]
	v_cndmask_b32_e64 v46, v247, v46, s[0:1]
	v_cndmask_b32_e64 v47, v247, v47, s[0:1]
	v_cndmask_b32_e64 v48, v247, v48, s[0:1]
	v_cndmask_b32_e64 v65, v247, v49, s[0:1]
	v_cndmask_b32_e64 v49, v247, v0, s[0:1]

; #define MFMA32(a, b, c) __builtin_amdgcn_mfma_f32_32x32x16_bf16((a), (b), (c), 0, 0, 0)
; DI void qk_tile(const bf16_t* KT, const bf16x8 (&qf)[4], int qi, int hl, f32x16& sc0, f32x16& sc1) {
; #pragma unroll
;     for (int i = 0; i < 16; ++i) { sc0[i] = 0.f; sc1[i] = 0.f; }
; #pragma unroll
;     for (int s = 0; s < 4; ++s) {
;         const bf16x8 k0 = *(const bf16x8*)(KT + qi * KTS + 16 * s + 8 * hl), k1 = *(const bf16x8*)(KT + (32 + qi) * KTS + 16 * s + 8 * hl);
;         sc0 = MFMA32(k0, qf[s], sc0); sc1 = MFMA32(k1, qf[s], sc1);
;     }
; __device__ __forceinline__ void nsa_item(unsigned char* smem, CP p, int L, int b, int g, int qb, int ocol) {
;     ...
;             f32x16 sc0, sc1; qk_tile(KT, qf, qi, hl, sc0, sc1);
;             if (w == 0) mask_tile<false, false, true, false>(sc0, sc1, lut, qpos, k0, hl, true, QS);
;             else if (w == 1) mask_tile<false, false, false, false>(sc0, sc1, lut, qpos, k0, hl, true, QS);
;             else if (w < 4) mask_tile<true, false, false, false>(sc0, sc1, lut, qpos, k0, hl, true, QS);
;             else mask_tile<true, true, false, false>(sc0, sc1, lut, qpos, k0, hl, true, QS);
.LBB0_791:
	s_or_b64 exec, exec, s[0:1]
	ds_read_b128 v[180:183], v154
	ds_read_b128 v[184:187], v154 offset:32
	ds_read_b128 v[188:191], v154 offset:4608
	ds_read_b128 v[216:219], v154 offset:4640
	ds_read_b128 v[220:223], v154 offset:64
	ds_read_b128 v[224:227], v154 offset:4672
	ds_read_b128 v[228:231], v154 offset:96
	ds_read_b128 v[232:235], v154 offset:4704
	v_cmp_lt_i32_e64 s[0:1], 0, v153
	s_mov_b64 s[6:7], 0
	s_mov_b64 s[10:11], 0
	s_waitcnt lgkmcnt(7)
	v_mfma_f32_32x32x16_bf16 v[50:65], v[180:183], v[98:101], 0
	s_waitcnt lgkmcnt(6)
	v_mfma_f32_32x32x16_bf16 v[50:65], v[184:187], v[102:105], v[50:65]
	s_waitcnt lgkmcnt(5)
	v_mfma_f32_32x32x16_bf16 v[34:49], v[188:191], v[98:101], 0
	s_waitcnt lgkmcnt(4)
	v_mfma_f32_32x32x16_bf16 v[34:49], v[216:219], v[102:105], v[34:49]
	s_waitcnt lgkmcnt(3)
	v_mfma_f32_32x32x16_bf16 v[50:65], v[220:223], v[106:109], v[50:65]
	s_waitcnt lgkmcnt(2)
	v_mfma_f32_32x32x16_bf16 v[34:49], v[224:227], v[106:109], v[34:49]
	s_waitcnt lgkmcnt(1)
	v_mfma_f32_32x32x16_bf16 v[50:65], v[228:231], v[110:113], v[50:65]
	s_waitcnt lgkmcnt(0)
	v_mfma_f32_32x32x16_bf16 v[34:49], v[232:235], v[110:113], v[34:49]
	s_and_saveexec_b64 s[8:9], s[0:1]
	s_xor_b64 s[8:9], exec, s[8:9]
	s_cbranch_execz .LBB0_795
	v_cmp_eq_u32_e64 s[0:1], 1, v153
	s_mov_b64 s[12:13], -1
	s_and_saveexec_b64 s[10:11], s[0:1]
	s_cbranch_execz .LBB0_794
	ds_read_b32 v0, v129 offset:18944
	s_mov_b32 s0, 0x3e38aa3b
	s_xor_b64 s[12:13], exec, -1
	s_waitcnt lgkmcnt(0)
	v_pk_fma_f32 v[94:95], v[64:65], s[0:1], v[0:1] op_sel_hi:[1,0,0]
	v_pk_fma_f32 v[96:97], v[62:63], s[0:1], v[0:1] op_sel_hi:[1,0,0]
	v_pk_fma_f32 v[114:115], v[60:61], s[0:1], v[0:1] op_sel_hi:[1,0,0]
	v_pk_fma_f32 v[130:131], v[58:59], s[0:1], v[0:1] op_sel_hi:[1,0,0]
	v_pk_fma_f32 v[120:121], v[56:57], s[0:1], v[0:1] op_sel_hi:[1,0,0]
	v_pk_fma_f32 v[118:119], v[54:55], s[0:1], v[0:1] op_sel_hi:[1,0,0]
	v_pk_fma_f32 v[116:117], v[52:53], s[0:1], v[0:1] op_sel_hi:[1,0,0]
	v_pk_fma_f32 v[92:93], v[50:51], s[0:1], v[0:1] op_sel_hi:[1,0,0]
	v_pk_fma_f32 v[80:81], v[48:49], s[0:1], v[0:1] op_sel_hi:[1,0,0]
	v_pk_fma_f32 v[78:79], v[46:47], s[0:1], v[0:1] op_sel_hi:[1,0,0]
	v_pk_fma_f32 v[76:77], v[44:45], s[0:1], v[0:1] op_sel_hi:[1,0,0]
	v_pk_fma_f32 v[74:75], v[42:43], s[0:1], v[0:1] op_sel_hi:[1,0,0]
	v_pk_fma_f32 v[72:73], v[40:41], s[0:1], v[0:1] op_sel_hi:[1,0,0]
	v_pk_fma_f32 v[70:71], v[38:39], s[0:1], v[0:1] op_sel_hi:[1,0,0]
	v_pk_fma_f32 v[68:69], v[36:37], s[0:1], v[0:1] op_sel_hi:[1,0,0]
	v_pk_fma_f32 v[66:67], v[34:35], s[0:1], v[0:1] op_sel_hi:[1,0,0]
